# MIX MFMA section: LDS operand reads software-pipelined two k-steps ahead with counted lgkmcnt (was read-wait-mfma per step)
# speedup vs baseline: 1.0192x; 1.0036x over previous
.Lmy_mix0_wdone:
	s_waitcnt vmcnt(0)
	s_waitcnt lgkmcnt(0)
	s_barrier
	s_lshl_b32 s8, s1, 1
	s_mov_b32 s9, s5
	v_or_b32_e32 v94, s91, v65
	v_or_b32_e32 v79, s4, v65
	v_ashrrev_i32_e32 v95, 31, v94
	v_lshlrev_b32_e32 v79, 2, v79
	v_lshlrev_b64 v[94:95], 12, v[94:95]
	s_add_i32 s90, s90, s0
	s_add_i32 s85, s85, s92
	global_load_dword v79, v79, s[96:97]
	ds_read_b64_tr_b16 v[196:197], v116
	ds_read_b64_tr_b16 v[198:199], v116 offset:2048
	ds_read_b128 v[132:135], v117
	ds_read_b128 v[136:139], v117 offset:8192
	ds_read_b128 v[140:143], v117 offset:16384
	ds_read_b128 v[144:147], v117 offset:24576
	ds_read_b64_tr_b16 v[200:201], v116 offset:8192
	ds_read_b64_tr_b16 v[202:203], v116 offset:10240
	ds_read_b128 v[148:151], v118
	ds_read_b128 v[152:155], v118 offset:8192
	ds_read_b128 v[156:159], v118 offset:16384
	ds_read_b128 v[160:163], v118 offset:24576
	s_waitcnt lgkmcnt(6)
	ds_read_b64_tr_b16 v[204:205], v116 offset:16384
	ds_read_b64_tr_b16 v[206:207], v116 offset:18432
	ds_read_b128 v[168:171], v119 offset:8192
	ds_read_b128 v[172:175], v119 offset:16384
	ds_read_b128 v[176:179], v119 offset:24576
	v_mfma_f32_32x32x16_bf16 v[48:63], v[196:199], v[132:135], 0
	v_mfma_f32_32x32x16_bf16 v[32:47], v[196:199], v[136:139], 0
	v_mfma_f32_32x32x16_bf16 v[16:31], v[196:199], v[140:143], 0
	v_mfma_f32_32x32x16_bf16 v[0:15], v[196:199], v[144:147], 0
	s_waitcnt lgkmcnt(5)
	ds_read_b64_tr_b16 v[196:197], v116 offset:24576
	ds_read_b64_tr_b16 v[198:199], v116 offset:26624
	ds_read_b128 v[136:139], v120 offset:8192
	ds_read_b128 v[140:143], v120 offset:16384
	ds_read_b128 v[144:147], v120 offset:24576
	v_mfma_f32_32x32x16_bf16 v[48:63], v[200:203], v[148:151], v[48:63]
	v_mfma_f32_32x32x16_bf16 v[32:47], v[200:203], v[152:155], v[32:47]
	v_mfma_f32_32x32x16_bf16 v[16:31], v[200:203], v[156:159], v[16:31]
	v_mfma_f32_32x32x16_bf16 v[0:15], v[200:203], v[160:163], v[0:15]
	s_waitcnt lgkmcnt(5)
	ds_read_b64_tr_b16 v[200:201], v116 offset:32768
	ds_read_b64_tr_b16 v[202:203], v116 offset:34816
	ds_read_b128 v[156:159], v121 offset:16384
	ds_read_b128 v[160:163], v121 offset:24576
	v_mfma_f32_32x32x16_bf16 v[32:47], v[204:207], v[168:171], v[32:47]
	v_mfma_f32_32x32x16_bf16 v[16:31], v[204:207], v[172:175], v[16:31]
	v_mfma_f32_32x32x16_bf16 v[0:15], v[204:207], v[176:179], v[0:15]
	s_waitcnt lgkmcnt(4)
	ds_read_b64_tr_b16 v[204:205], v116 offset:40960
	ds_read_b64_tr_b16 v[206:207], v116 offset:43008
	ds_read_b128 v[172:175], v122 offset:16384
	ds_read_b128 v[176:179], v122 offset:24576
	v_mfma_f32_32x32x16_bf16 v[32:47], v[196:199], v[136:139], v[32:47]
	v_mfma_f32_32x32x16_bf16 v[16:31], v[196:199], v[140:143], v[16:31]
	v_mfma_f32_32x32x16_bf16 v[0:15], v[196:199], v[144:147], v[0:15]
	s_waitcnt lgkmcnt(4)
	ds_read_b64_tr_b16 v[196:197], v116 offset:49152
	ds_read_b64_tr_b16 v[198:199], v116 offset:51200
	ds_read_b128 v[144:147], v123 offset:24576
	v_mfma_f32_32x32x16_bf16 v[16:31], v[200:203], v[156:159], v[16:31]
	v_mfma_f32_32x32x16_bf16 v[0:15], v[200:203], v[160:163], v[0:15]
	s_waitcnt lgkmcnt(3)
	ds_read_b64_tr_b16 v[200:201], v116 offset:57344
	ds_read_b64_tr_b16 v[202:203], v116 offset:59392
	ds_read_b128 v[160:163], v124 offset:24576
	v_mfma_f32_32x32x16_bf16 v[16:31], v[204:207], v[172:175], v[16:31]
	v_mfma_f32_32x32x16_bf16 v[0:15], v[204:207], v[176:179], v[0:15]
	s_waitcnt lgkmcnt(3)
	v_mfma_f32_32x32x16_bf16 v[0:15], v[196:199], v[144:147], v[0:15]
	s_waitcnt lgkmcnt(0)
	v_mfma_f32_32x32x16_bf16 v[0:15], v[200:203], v[160:163], v[0:15]
	v_lshl_add_u64 v[92:93], v[72:73], 0, s[8:9]
	s_lshl_b32 s8, s1, 2
	v_lshl_add_u64 v[90:91], v[74:75], 0, s[8:9]
	v_lshl_add_u64 v[94:95], v[92:93], 0, v[94:95]
	s_cmpk_gt_i32 s90, 0x3ff
	global_load_dwordx4 v[136:139], v[90:91], off
	global_load_dwordx4 v[140:143], v[90:91], off offset:32
	global_load_dwordx4 v[144:147], v[90:91], off offset:64
	global_load_dwordx4 v[148:151], v[90:91], off offset:96
	global_load_dwordx2 v[160:161], v[94:95], off
	global_load_dwordx2 v[162:163], v[94:95], off offset:16
	global_load_dwordx2 v[164:165], v[94:95], off offset:32
	global_load_dwordx2 v[166:167], v[94:95], off offset:48
	v_add_lshl_u32 v132, s4, v65, 2
	v_or_b32_e32 v152, s91, v108
	v_ashrrev_i32_e32 v153, 31, v152
	v_lshlrev_b64 v[152:153], 12, v[152:153]
	v_lshl_add_u64 v[152:153], v[92:93], 0, v[152:153]
	global_load_dword v133, v132, s[96:97] offset:128
	global_load_dwordx2 v[168:169], v[152:153], off
	global_load_dwordx2 v[170:171], v[152:153], off offset:16
	global_load_dwordx2 v[172:173], v[152:153], off offset:32
	global_load_dwordx2 v[174:175], v[152:153], off offset:48
	v_or_b32_e32 v154, s91, v109
	v_ashrrev_i32_e32 v155, 31, v154
	v_lshlrev_b64 v[154:155], 12, v[154:155]
	v_lshl_add_u64 v[154:155], v[92:93], 0, v[154:155]
	global_load_dword v134, v132, s[96:97] offset:256
	global_load_dwordx2 v[176:177], v[154:155], off
	global_load_dwordx2 v[178:179], v[154:155], off offset:16
	global_load_dwordx2 v[180:181], v[154:155], off offset:32
	global_load_dwordx2 v[182:183], v[154:155], off offset:48
	v_or_b32_e32 v156, s91, v110
	v_ashrrev_i32_e32 v157, 31, v156
	v_lshlrev_b64 v[156:157], 12, v[156:157]
	v_lshl_add_u64 v[156:157], v[92:93], 0, v[156:157]
	global_load_dword v135, v132, s[96:97] offset:384
	global_load_dwordx2 v[184:185], v[156:157], off
	global_load_dwordx2 v[186:187], v[156:157], off offset:16
	global_load_dwordx2 v[188:189], v[156:157], off offset:32
	global_load_dwordx2 v[190:191], v[156:157], off offset:48
	s_waitcnt vmcnt(15)
	v_fma_f32 v48, v48, v136, v79
	v_lshlrev_b32_e32 v192, 16, v160
	v_and_b32_e32 v193, 0xffff0000, v160
	v_fma_f32 v49, v49, v137, v79
	v_mul_f32_e32 v48, v48, v192
	v_mul_f32_e32 v49, v49, v193
	v_lshlrev_b32_e32 v194, 16, v161
	v_and_b32_e32 v195, 0xffff0000, v161
	v_fma_f32 v50, v50, v138, v79
	v_fma_f32 v51, v51, v139, v79
	v_mul_f32_e32 v50, v50, v194
	v_mul_f32_e32 v51, v51, v195
	v_cvt_pk_bf16_f32 v48, v48, v49
	v_cvt_pk_bf16_f32 v49, v50, v51
	global_store_dwordx2 v[94:95], v[48:49], off
	v_fma_f32 v52, v52, v140, v79
	v_lshlrev_b32_e32 v192, 16, v162
	v_and_b32_e32 v193, 0xffff0000, v162
	v_fma_f32 v53, v53, v141, v79
	v_mul_f32_e32 v52, v52, v192
	v_mul_f32_e32 v53, v53, v193
	v_lshlrev_b32_e32 v194, 16, v163
	v_and_b32_e32 v195, 0xffff0000, v163
	v_fma_f32 v54, v54, v142, v79
	v_fma_f32 v55, v55, v143, v79
	v_mul_f32_e32 v54, v54, v194
	v_mul_f32_e32 v55, v55, v195
	v_cvt_pk_bf16_f32 v52, v52, v53
	v_cvt_pk_bf16_f32 v53, v54, v55
	global_store_dwordx2 v[94:95], v[52:53], off offset:16
	v_fma_f32 v56, v56, v144, v79
	v_lshlrev_b32_e32 v192, 16, v164
	v_and_b32_e32 v193, 0xffff0000, v164
	v_fma_f32 v57, v57, v145, v79
	v_mul_f32_e32 v56, v56, v192
	v_mul_f32_e32 v57, v57, v193
	v_lshlrev_b32_e32 v194, 16, v165
	v_and_b32_e32 v195, 0xffff0000, v165
	v_fma_f32 v58, v58, v146, v79
	v_fma_f32 v59, v59, v147, v79
	v_mul_f32_e32 v58, v58, v194
	v_mul_f32_e32 v59, v59, v195
	v_cvt_pk_bf16_f32 v56, v56, v57
	v_cvt_pk_bf16_f32 v57, v58, v59
	global_store_dwordx2 v[94:95], v[56:57], off offset:32
	v_fma_f32 v60, v60, v148, v79
	v_lshlrev_b32_e32 v192, 16, v166
	v_and_b32_e32 v193, 0xffff0000, v166
	v_fma_f32 v61, v61, v149, v79
	v_mul_f32_e32 v60, v60, v192
	v_mul_f32_e32 v61, v61, v193
	v_lshlrev_b32_e32 v194, 16, v167
	v_and_b32_e32 v195, 0xffff0000, v167
	v_fma_f32 v62, v62, v150, v79
	v_fma_f32 v63, v63, v151, v79
	v_mul_f32_e32 v62, v62, v194
	v_mul_f32_e32 v63, v63, v195
	v_cvt_pk_bf16_f32 v60, v60, v61
	v_cvt_pk_bf16_f32 v61, v62, v63
	global_store_dwordx2 v[94:95], v[60:61], off offset:48
	s_waitcnt vmcnt(14)
	v_fma_f32 v32, v32, v136, v133
	v_lshlrev_b32_e32 v192, 16, v168
	v_and_b32_e32 v193, 0xffff0000, v168
	v_fma_f32 v33, v33, v137, v133
	v_mul_f32_e32 v32, v32, v192
	v_mul_f32_e32 v33, v33, v193
	v_lshlrev_b32_e32 v194, 16, v169
	v_and_b32_e32 v195, 0xffff0000, v169
	v_fma_f32 v34, v34, v138, v133
	v_fma_f32 v35, v35, v139, v133
	v_mul_f32_e32 v34, v34, v194
	v_mul_f32_e32 v35, v35, v195
	v_cvt_pk_bf16_f32 v32, v32, v33
	v_cvt_pk_bf16_f32 v33, v34, v35
	global_store_dwordx2 v[152:153], v[32:33], off
	v_fma_f32 v36, v36, v140, v133
	v_lshlrev_b32_e32 v192, 16, v170
	v_and_b32_e32 v193, 0xffff0000, v170
	v_fma_f32 v37, v37, v141, v133
	v_mul_f32_e32 v36, v36, v192
	v_mul_f32_e32 v37, v37, v193
	v_lshlrev_b32_e32 v194, 16, v171
	v_and_b32_e32 v195, 0xffff0000, v171
	v_fma_f32 v38, v38, v142, v133
	v_fma_f32 v39, v39, v143, v133
	v_mul_f32_e32 v38, v38, v194
	v_mul_f32_e32 v39, v39, v195
	v_cvt_pk_bf16_f32 v36, v36, v37
	v_cvt_pk_bf16_f32 v37, v38, v39
	global_store_dwordx2 v[152:153], v[36:37], off offset:16
	v_fma_f32 v40, v40, v144, v133
	v_lshlrev_b32_e32 v192, 16, v172
	v_and_b32_e32 v193, 0xffff0000, v172
	v_fma_f32 v41, v41, v145, v133
	v_mul_f32_e32 v40, v40, v192
	v_mul_f32_e32 v41, v41, v193
	v_lshlrev_b32_e32 v194, 16, v173
	v_and_b32_e32 v195, 0xffff0000, v173
	v_fma_f32 v42, v42, v146, v133
	v_fma_f32 v43, v43, v147, v133
	v_mul_f32_e32 v42, v42, v194
	v_mul_f32_e32 v43, v43, v195
	v_cvt_pk_bf16_f32 v40, v40, v41
	v_cvt_pk_bf16_f32 v41, v42, v43
	global_store_dwordx2 v[152:153], v[40:41], off offset:32
	v_fma_f32 v44, v44, v148, v133
	v_lshlrev_b32_e32 v192, 16, v174
	v_and_b32_e32 v193, 0xffff0000, v174
	v_fma_f32 v45, v45, v149, v133
	v_mul_f32_e32 v44, v44, v192
	v_mul_f32_e32 v45, v45, v193
	v_lshlrev_b32_e32 v194, 16, v175
	v_and_b32_e32 v195, 0xffff0000, v175
	v_fma_f32 v46, v46, v150, v133
	v_fma_f32 v47, v47, v151, v133
	v_mul_f32_e32 v46, v46, v194
	v_mul_f32_e32 v47, v47, v195
	v_cvt_pk_bf16_f32 v44, v44, v45
	v_cvt_pk_bf16_f32 v45, v46, v47
	global_store_dwordx2 v[152:153], v[44:45], off offset:48
	s_waitcnt vmcnt(13)
	v_fma_f32 v16, v16, v136, v134
	v_lshlrev_b32_e32 v192, 16, v176
	v_and_b32_e32 v193, 0xffff0000, v176
	v_fma_f32 v17, v17, v137, v134
	v_mul_f32_e32 v16, v16, v192
	v_mul_f32_e32 v17, v17, v193
	v_lshlrev_b32_e32 v194, 16, v177
	v_and_b32_e32 v195, 0xffff0000, v177
	v_fma_f32 v18, v18, v138, v134
	v_fma_f32 v19, v19, v139, v134
	v_mul_f32_e32 v18, v18, v194
	v_mul_f32_e32 v19, v19, v195
	v_cvt_pk_bf16_f32 v16, v16, v17
	v_cvt_pk_bf16_f32 v17, v18, v19
	global_store_dwordx2 v[154:155], v[16:17], off
	v_fma_f32 v20, v20, v140, v134
	v_lshlrev_b32_e32 v192, 16, v178
	v_and_b32_e32 v193, 0xffff0000, v178
	v_fma_f32 v21, v21, v141, v134
	v_mul_f32_e32 v20, v20, v192
	v_mul_f32_e32 v21, v21, v193
	v_lshlrev_b32_e32 v194, 16, v179
	v_and_b32_e32 v195, 0xffff0000, v179
	v_fma_f32 v22, v22, v142, v134
	v_fma_f32 v23, v23, v143, v134
	v_mul_f32_e32 v22, v22, v194
	v_mul_f32_e32 v23, v23, v195
	v_cvt_pk_bf16_f32 v20, v20, v21
	v_cvt_pk_bf16_f32 v21, v22, v23
	global_store_dwordx2 v[154:155], v[20:21], off offset:16
	v_fma_f32 v24, v24, v144, v134
	v_lshlrev_b32_e32 v192, 16, v180
	v_and_b32_e32 v193, 0xffff0000, v180
	v_fma_f32 v25, v25, v145, v134
	v_mul_f32_e32 v24, v24, v192
	v_mul_f32_e32 v25, v25, v193
	v_lshlrev_b32_e32 v194, 16, v181
	v_and_b32_e32 v195, 0xffff0000, v181
	v_fma_f32 v26, v26, v146, v134
	v_fma_f32 v27, v27, v147, v134
	v_mul_f32_e32 v26, v26, v194
	v_mul_f32_e32 v27, v27, v195
	v_cvt_pk_bf16_f32 v24, v24, v25
	v_cvt_pk_bf16_f32 v25, v26, v27
	global_store_dwordx2 v[154:155], v[24:25], off offset:32
	v_fma_f32 v28, v28, v148, v134
	v_lshlrev_b32_e32 v192, 16, v182
	v_and_b32_e32 v193, 0xffff0000, v182
	v_fma_f32 v29, v29, v149, v134
	v_mul_f32_e32 v28, v28, v192
	v_mul_f32_e32 v29, v29, v193
	v_lshlrev_b32_e32 v194, 16, v183
	v_and_b32_e32 v195, 0xffff0000, v183
	v_fma_f32 v30, v30, v150, v134
	v_fma_f32 v31, v31, v151, v134
	v_mul_f32_e32 v30, v30, v194
	v_mul_f32_e32 v31, v31, v195
	v_cvt_pk_bf16_f32 v28, v28, v29
	v_cvt_pk_bf16_f32 v29, v30, v31
	global_store_dwordx2 v[154:155], v[28:29], off offset:48
	s_waitcnt vmcnt(12)
	v_fma_f32 v0, v0, v136, v135
	v_lshlrev_b32_e32 v192, 16, v184
	v_and_b32_e32 v193, 0xffff0000, v184
	v_fma_f32 v1, v1, v137, v135
	v_mul_f32_e32 v0, v0, v192
	v_mul_f32_e32 v1, v1, v193
	v_lshlrev_b32_e32 v194, 16, v185
	v_and_b32_e32 v195, 0xffff0000, v185
	v_fma_f32 v2, v2, v138, v135
	v_fma_f32 v3, v3, v139, v135
	v_mul_f32_e32 v2, v2, v194
	v_mul_f32_e32 v3, v3, v195
	v_cvt_pk_bf16_f32 v0, v0, v1
	v_cvt_pk_bf16_f32 v1, v2, v3
	global_store_dwordx2 v[156:157], v[0:1], off
	v_fma_f32 v4, v4, v140, v135
	v_lshlrev_b32_e32 v192, 16, v186
	v_and_b32_e32 v193, 0xffff0000, v186
	v_fma_f32 v5, v5, v141, v135
	v_mul_f32_e32 v4, v4, v192
	v_mul_f32_e32 v5, v5, v193
	v_lshlrev_b32_e32 v194, 16, v187
	v_and_b32_e32 v195, 0xffff0000, v187
	v_fma_f32 v6, v6, v142, v135
	v_fma_f32 v7, v7, v143, v135
	v_mul_f32_e32 v6, v6, v194
	v_mul_f32_e32 v7, v7, v195
	v_cvt_pk_bf16_f32 v4, v4, v5
	v_cvt_pk_bf16_f32 v5, v6, v7
	global_store_dwordx2 v[156:157], v[4:5], off offset:16
	v_fma_f32 v8, v8, v144, v135
	v_lshlrev_b32_e32 v192, 16, v188
	v_and_b32_e32 v193, 0xffff0000, v188
	v_fma_f32 v9, v9, v145, v135
	v_mul_f32_e32 v8, v8, v192
	v_mul_f32_e32 v9, v9, v193
	v_lshlrev_b32_e32 v194, 16, v189
	v_and_b32_e32 v195, 0xffff0000, v189
	v_fma_f32 v10, v10, v146, v135
	v_fma_f32 v11, v11, v147, v135
	v_mul_f32_e32 v10, v10, v194
	v_mul_f32_e32 v11, v11, v195
	v_cvt_pk_bf16_f32 v8, v8, v9
	v_cvt_pk_bf16_f32 v9, v10, v11
	global_store_dwordx2 v[156:157], v[8:9], off offset:32
	v_fma_f32 v12, v12, v148, v135
	v_lshlrev_b32_e32 v192, 16, v190
	v_and_b32_e32 v193, 0xffff0000, v190
	v_fma_f32 v13, v13, v149, v135
	v_mul_f32_e32 v12, v12, v192
	v_mul_f32_e32 v13, v13, v193
	v_lshlrev_b32_e32 v194, 16, v191
	v_and_b32_e32 v195, 0xffff0000, v191
	v_fma_f32 v14, v14, v150, v135
	v_fma_f32 v15, v15, v151, v135
	v_mul_f32_e32 v14, v14, v194
	v_mul_f32_e32 v15, v15, v195
	v_cvt_pk_bf16_f32 v12, v12, v13
	v_cvt_pk_bf16_f32 v13, v14, v15
	global_store_dwordx2 v[156:157], v[12:13], off offset:48
	s_barrier
	s_cbranch_scc1 .LBB0_305

.Lmy_mix1_wdone:
	s_waitcnt vmcnt(0)
	s_waitcnt lgkmcnt(0)
	s_barrier
	s_lshl_b32 s78, s1, 1
	s_mov_b32 s79, s5
	v_or_b32_e32 v94, s90, v65
	v_or_b32_e32 v79, s4, v65
	v_ashrrev_i32_e32 v95, 31, v94
	v_lshlrev_b32_e32 v79, 2, v79
	v_lshlrev_b64 v[94:95], 12, v[94:95]
	s_add_i32 s93, s93, s0
	s_add_i32 s85, s85, s94
	global_load_dword v79, v79, s[8:9]
	ds_read_b64_tr_b16 v[196:197], v116
	ds_read_b64_tr_b16 v[198:199], v116 offset:2048
	ds_read_b128 v[132:135], v117
	ds_read_b128 v[136:139], v117 offset:8192
	ds_read_b128 v[140:143], v117 offset:16384
	ds_read_b128 v[144:147], v117 offset:24576
	ds_read_b64_tr_b16 v[200:201], v116 offset:8192
	ds_read_b64_tr_b16 v[202:203], v116 offset:10240
	ds_read_b128 v[148:151], v118
	ds_read_b128 v[152:155], v118 offset:8192
	ds_read_b128 v[156:159], v118 offset:16384
	ds_read_b128 v[160:163], v118 offset:24576
	s_waitcnt lgkmcnt(6)
	ds_read_b64_tr_b16 v[204:205], v116 offset:16384
	ds_read_b64_tr_b16 v[206:207], v116 offset:18432
	ds_read_b128 v[168:171], v119 offset:8192
	ds_read_b128 v[172:175], v119 offset:16384
	ds_read_b128 v[176:179], v119 offset:24576
	v_mfma_f32_32x32x16_bf16 v[48:63], v[196:199], v[132:135], 0
	v_mfma_f32_32x32x16_bf16 v[32:47], v[196:199], v[136:139], 0
	v_mfma_f32_32x32x16_bf16 v[16:31], v[196:199], v[140:143], 0
	v_mfma_f32_32x32x16_bf16 v[0:15], v[196:199], v[144:147], 0
	s_waitcnt lgkmcnt(5)
	ds_read_b64_tr_b16 v[196:197], v116 offset:24576
	ds_read_b64_tr_b16 v[198:199], v116 offset:26624
	ds_read_b128 v[136:139], v120 offset:8192
	ds_read_b128 v[140:143], v120 offset:16384
	ds_read_b128 v[144:147], v120 offset:24576
	v_mfma_f32_32x32x16_bf16 v[48:63], v[200:203], v[148:151], v[48:63]
	v_mfma_f32_32x32x16_bf16 v[32:47], v[200:203], v[152:155], v[32:47]
	v_mfma_f32_32x32x16_bf16 v[16:31], v[200:203], v[156:159], v[16:31]
	v_mfma_f32_32x32x16_bf16 v[0:15], v[200:203], v[160:163], v[0:15]
	s_waitcnt lgkmcnt(5)
	ds_read_b64_tr_b16 v[200:201], v116 offset:32768
	ds_read_b64_tr_b16 v[202:203], v116 offset:34816
	ds_read_b128 v[156:159], v121 offset:16384
	ds_read_b128 v[160:163], v121 offset:24576
	v_mfma_f32_32x32x16_bf16 v[32:47], v[204:207], v[168:171], v[32:47]
	v_mfma_f32_32x32x16_bf16 v[16:31], v[204:207], v[172:175], v[16:31]
	v_mfma_f32_32x32x16_bf16 v[0:15], v[204:207], v[176:179], v[0:15]
	s_waitcnt lgkmcnt(4)
	ds_read_b64_tr_b16 v[204:205], v116 offset:40960
	ds_read_b64_tr_b16 v[206:207], v116 offset:43008
	ds_read_b128 v[172:175], v122 offset:16384
	ds_read_b128 v[176:179], v122 offset:24576
	v_mfma_f32_32x32x16_bf16 v[32:47], v[196:199], v[136:139], v[32:47]
	v_mfma_f32_32x32x16_bf16 v[16:31], v[196:199], v[140:143], v[16:31]
	v_mfma_f32_32x32x16_bf16 v[0:15], v[196:199], v[144:147], v[0:15]
	s_waitcnt lgkmcnt(4)
	ds_read_b64_tr_b16 v[196:197], v116 offset:49152
	ds_read_b64_tr_b16 v[198:199], v116 offset:51200
	ds_read_b128 v[144:147], v123 offset:24576
	v_mfma_f32_32x32x16_bf16 v[16:31], v[200:203], v[156:159], v[16:31]
	v_mfma_f32_32x32x16_bf16 v[0:15], v[200:203], v[160:163], v[0:15]
	s_waitcnt lgkmcnt(3)
	ds_read_b64_tr_b16 v[200:201], v116 offset:57344
	ds_read_b64_tr_b16 v[202:203], v116 offset:59392
	ds_read_b128 v[160:163], v124 offset:24576
	v_mfma_f32_32x32x16_bf16 v[16:31], v[204:207], v[172:175], v[16:31]
	v_mfma_f32_32x32x16_bf16 v[0:15], v[204:207], v[176:179], v[0:15]
	s_waitcnt lgkmcnt(3)
	v_mfma_f32_32x32x16_bf16 v[0:15], v[196:199], v[144:147], v[0:15]
	s_waitcnt lgkmcnt(0)
	v_mfma_f32_32x32x16_bf16 v[0:15], v[200:203], v[160:163], v[0:15]
	v_lshl_add_u64 v[92:93], v[72:73], 0, s[78:79]
	s_lshl_b32 s78, s1, 2
	v_lshl_add_u64 v[90:91], v[74:75], 0, s[78:79]
	v_lshl_add_u64 v[94:95], v[92:93], 0, v[94:95]
	s_cmpk_gt_i32 s93, 0x3ff
	global_load_dwordx4 v[136:139], v[90:91], off
	global_load_dwordx4 v[140:143], v[90:91], off offset:32
	global_load_dwordx4 v[144:147], v[90:91], off offset:64
	global_load_dwordx4 v[148:151], v[90:91], off offset:96
	global_load_dwordx2 v[160:161], v[94:95], off
	global_load_dwordx2 v[162:163], v[94:95], off offset:16
	global_load_dwordx2 v[164:165], v[94:95], off offset:32
	global_load_dwordx2 v[166:167], v[94:95], off offset:48
	v_or_b32_e32 v152, s90, v108
	v_ashrrev_i32_e32 v153, 31, v152
	v_lshlrev_b64 v[152:153], 12, v[152:153]
	v_lshl_add_u64 v[152:153], v[92:93], 0, v[152:153]
	v_or_b32_e32 v132, s4, v108
	v_lshlrev_b32_e32 v132, 2, v132
	global_load_dword v133, v132, s[8:9]
	global_load_dwordx2 v[168:169], v[152:153], off
	global_load_dwordx2 v[170:171], v[152:153], off offset:16
	global_load_dwordx2 v[172:173], v[152:153], off offset:32
	global_load_dwordx2 v[174:175], v[152:153], off offset:48
	v_or_b32_e32 v154, s90, v109
	v_ashrrev_i32_e32 v155, 31, v154
	v_lshlrev_b64 v[154:155], 12, v[154:155]
	v_lshl_add_u64 v[154:155], v[92:93], 0, v[154:155]
	v_or_b32_e32 v132, s4, v109
	v_lshlrev_b32_e32 v132, 2, v132
	global_load_dword v134, v132, s[8:9]
	global_load_dwordx2 v[176:177], v[154:155], off
	global_load_dwordx2 v[178:179], v[154:155], off offset:16
	global_load_dwordx2 v[180:181], v[154:155], off offset:32
	global_load_dwordx2 v[182:183], v[154:155], off offset:48
	v_or_b32_e32 v156, s90, v110
	v_ashrrev_i32_e32 v157, 31, v156
	v_lshlrev_b64 v[156:157], 12, v[156:157]
	v_lshl_add_u64 v[156:157], v[92:93], 0, v[156:157]
	v_or_b32_e32 v132, s4, v110
	v_lshlrev_b32_e32 v132, 2, v132
	global_load_dword v135, v132, s[8:9]
	global_load_dwordx2 v[184:185], v[156:157], off
	global_load_dwordx2 v[186:187], v[156:157], off offset:16
	global_load_dwordx2 v[188:189], v[156:157], off offset:32
	global_load_dwordx2 v[190:191], v[156:157], off offset:48
	s_waitcnt vmcnt(15)
	v_fma_f32 v48, v48, v136, v79
	v_lshlrev_b32_e32 v192, 16, v160
	v_and_b32_e32 v193, 0xffff0000, v160
	v_fma_f32 v49, v49, v137, v79
	v_mul_f32_e32 v48, v48, v192
	v_mul_f32_e32 v49, v49, v193
	v_lshlrev_b32_e32 v194, 16, v161
	v_and_b32_e32 v195, 0xffff0000, v161
	v_fma_f32 v50, v50, v138, v79
	v_fma_f32 v51, v51, v139, v79
	v_mul_f32_e32 v50, v50, v194
	v_mul_f32_e32 v51, v51, v195
	v_cvt_pk_bf16_f32 v48, v48, v49
	v_cvt_pk_bf16_f32 v49, v50, v51
	global_store_dwordx2 v[94:95], v[48:49], off
	v_fma_f32 v52, v52, v140, v79
	v_lshlrev_b32_e32 v192, 16, v162
	v_and_b32_e32 v193, 0xffff0000, v162
	v_fma_f32 v53, v53, v141, v79
	v_mul_f32_e32 v52, v52, v192
	v_mul_f32_e32 v53, v53, v193
	v_lshlrev_b32_e32 v194, 16, v163
	v_and_b32_e32 v195, 0xffff0000, v163
	v_fma_f32 v54, v54, v142, v79
	v_fma_f32 v55, v55, v143, v79
	v_mul_f32_e32 v54, v54, v194
	v_mul_f32_e32 v55, v55, v195
	v_cvt_pk_bf16_f32 v52, v52, v53
	v_cvt_pk_bf16_f32 v53, v54, v55
	global_store_dwordx2 v[94:95], v[52:53], off offset:16
	v_fma_f32 v56, v56, v144, v79
	v_lshlrev_b32_e32 v192, 16, v164
	v_and_b32_e32 v193, 0xffff0000, v164
	v_fma_f32 v57, v57, v145, v79
	v_mul_f32_e32 v56, v56, v192
	v_mul_f32_e32 v57, v57, v193
	v_lshlrev_b32_e32 v194, 16, v165
	v_and_b32_e32 v195, 0xffff0000, v165
	v_fma_f32 v58, v58, v146, v79
	v_fma_f32 v59, v59, v147, v79
	v_mul_f32_e32 v58, v58, v194
	v_mul_f32_e32 v59, v59, v195
	v_cvt_pk_bf16_f32 v56, v56, v57
	v_cvt_pk_bf16_f32 v57, v58, v59
	global_store_dwordx2 v[94:95], v[56:57], off offset:32
	v_fma_f32 v60, v60, v148, v79
	v_lshlrev_b32_e32 v192, 16, v166
	v_and_b32_e32 v193, 0xffff0000, v166
	v_fma_f32 v61, v61, v149, v79
	v_mul_f32_e32 v60, v60, v192
	v_mul_f32_e32 v61, v61, v193
	v_lshlrev_b32_e32 v194, 16, v167
	v_and_b32_e32 v195, 0xffff0000, v167
	v_fma_f32 v62, v62, v150, v79
	v_fma_f32 v63, v63, v151, v79
	v_mul_f32_e32 v62, v62, v194
	v_mul_f32_e32 v63, v63, v195
	v_cvt_pk_bf16_f32 v60, v60, v61
	v_cvt_pk_bf16_f32 v61, v62, v63
	global_store_dwordx2 v[94:95], v[60:61], off offset:48
	s_waitcnt vmcnt(14)
	v_fma_f32 v32, v32, v136, v133
	v_lshlrev_b32_e32 v192, 16, v168
	v_and_b32_e32 v193, 0xffff0000, v168
	v_fma_f32 v33, v33, v137, v133
	v_mul_f32_e32 v32, v32, v192
	v_mul_f32_e32 v33, v33, v193
	v_lshlrev_b32_e32 v194, 16, v169
	v_and_b32_e32 v195, 0xffff0000, v169
	v_fma_f32 v34, v34, v138, v133
	v_fma_f32 v35, v35, v139, v133
	v_mul_f32_e32 v34, v34, v194
	v_mul_f32_e32 v35, v35, v195
	v_cvt_pk_bf16_f32 v32, v32, v33
	v_cvt_pk_bf16_f32 v33, v34, v35
	global_store_dwordx2 v[152:153], v[32:33], off
	v_fma_f32 v36, v36, v140, v133
	v_lshlrev_b32_e32 v192, 16, v170
	v_and_b32_e32 v193, 0xffff0000, v170
	v_fma_f32 v37, v37, v141, v133
	v_mul_f32_e32 v36, v36, v192
	v_mul_f32_e32 v37, v37, v193
	v_lshlrev_b32_e32 v194, 16, v171
	v_and_b32_e32 v195, 0xffff0000, v171
	v_fma_f32 v38, v38, v142, v133
	v_fma_f32 v39, v39, v143, v133
	v_mul_f32_e32 v38, v38, v194
	v_mul_f32_e32 v39, v39, v195
	v_cvt_pk_bf16_f32 v36, v36, v37
	v_cvt_pk_bf16_f32 v37, v38, v39
	global_store_dwordx2 v[152:153], v[36:37], off offset:16
	v_fma_f32 v40, v40, v144, v133
	v_lshlrev_b32_e32 v192, 16, v172
	v_and_b32_e32 v193, 0xffff0000, v172
	v_fma_f32 v41, v41, v145, v133
	v_mul_f32_e32 v40, v40, v192
	v_mul_f32_e32 v41, v41, v193
	v_lshlrev_b32_e32 v194, 16, v173
	v_and_b32_e32 v195, 0xffff0000, v173
	v_fma_f32 v42, v42, v146, v133
	v_fma_f32 v43, v43, v147, v133
	v_mul_f32_e32 v42, v42, v194
	v_mul_f32_e32 v43, v43, v195
	v_cvt_pk_bf16_f32 v40, v40, v41
	v_cvt_pk_bf16_f32 v41, v42, v43
	global_store_dwordx2 v[152:153], v[40:41], off offset:32
	v_fma_f32 v44, v44, v148, v133
	v_lshlrev_b32_e32 v192, 16, v174
	v_and_b32_e32 v193, 0xffff0000, v174
	v_fma_f32 v45, v45, v149, v133
	v_mul_f32_e32 v44, v44, v192
	v_mul_f32_e32 v45, v45, v193
	v_lshlrev_b32_e32 v194, 16, v175
	v_and_b32_e32 v195, 0xffff0000, v175
	v_fma_f32 v46, v46, v150, v133
	v_fma_f32 v47, v47, v151, v133
	v_mul_f32_e32 v46, v46, v194
	v_mul_f32_e32 v47, v47, v195
	v_cvt_pk_bf16_f32 v44, v44, v45
	v_cvt_pk_bf16_f32 v45, v46, v47
	global_store_dwordx2 v[152:153], v[44:45], off offset:48
	s_waitcnt vmcnt(13)
	v_fma_f32 v16, v16, v136, v134
	v_lshlrev_b32_e32 v192, 16, v176
	v_and_b32_e32 v193, 0xffff0000, v176
	v_fma_f32 v17, v17, v137, v134
	v_mul_f32_e32 v16, v16, v192
	v_mul_f32_e32 v17, v17, v193
	v_lshlrev_b32_e32 v194, 16, v177
	v_and_b32_e32 v195, 0xffff0000, v177
	v_fma_f32 v18, v18, v138, v134
	v_fma_f32 v19, v19, v139, v134
	v_mul_f32_e32 v18, v18, v194
	v_mul_f32_e32 v19, v19, v195
	v_cvt_pk_bf16_f32 v16, v16, v17
	v_cvt_pk_bf16_f32 v17, v18, v19
	global_store_dwordx2 v[154:155], v[16:17], off
	v_fma_f32 v20, v20, v140, v134
	v_lshlrev_b32_e32 v192, 16, v178
	v_and_b32_e32 v193, 0xffff0000, v178
	v_fma_f32 v21, v21, v141, v134
	v_mul_f32_e32 v20, v20, v192
	v_mul_f32_e32 v21, v21, v193
	v_lshlrev_b32_e32 v194, 16, v179
	v_and_b32_e32 v195, 0xffff0000, v179
	v_fma_f32 v22, v22, v142, v134
	v_fma_f32 v23, v23, v143, v134
	v_mul_f32_e32 v22, v22, v194
	v_mul_f32_e32 v23, v23, v195
	v_cvt_pk_bf16_f32 v20, v20, v21
	v_cvt_pk_bf16_f32 v21, v22, v23
	global_store_dwordx2 v[154:155], v[20:21], off offset:16
	v_fma_f32 v24, v24, v144, v134
	v_lshlrev_b32_e32 v192, 16, v180
	v_and_b32_e32 v193, 0xffff0000, v180
	v_fma_f32 v25, v25, v145, v134
	v_mul_f32_e32 v24, v24, v192
	v_mul_f32_e32 v25, v25, v193
	v_lshlrev_b32_e32 v194, 16, v181
	v_and_b32_e32 v195, 0xffff0000, v181
	v_fma_f32 v26, v26, v146, v134
	v_fma_f32 v27, v27, v147, v134
	v_mul_f32_e32 v26, v26, v194
	v_mul_f32_e32 v27, v27, v195
	v_cvt_pk_bf16_f32 v24, v24, v25
	v_cvt_pk_bf16_f32 v25, v26, v27
	global_store_dwordx2 v[154:155], v[24:25], off offset:32
	v_fma_f32 v28, v28, v148, v134
	v_lshlrev_b32_e32 v192, 16, v182
	v_and_b32_e32 v193, 0xffff0000, v182
	v_fma_f32 v29, v29, v149, v134
	v_mul_f32_e32 v28, v28, v192
	v_mul_f32_e32 v29, v29, v193
	v_lshlrev_b32_e32 v194, 16, v183
	v_and_b32_e32 v195, 0xffff0000, v183
	v_fma_f32 v30, v30, v150, v134
	v_fma_f32 v31, v31, v151, v134
	v_mul_f32_e32 v30, v30, v194
	v_mul_f32_e32 v31, v31, v195
	v_cvt_pk_bf16_f32 v28, v28, v29
	v_cvt_pk_bf16_f32 v29, v30, v31
	global_store_dwordx2 v[154:155], v[28:29], off offset:48
	s_waitcnt vmcnt(12)
	v_fma_f32 v0, v0, v136, v135
	v_lshlrev_b32_e32 v192, 16, v184
	v_and_b32_e32 v193, 0xffff0000, v184
	v_fma_f32 v1, v1, v137, v135
	v_mul_f32_e32 v0, v0, v192
	v_mul_f32_e32 v1, v1, v193
	v_lshlrev_b32_e32 v194, 16, v185
	v_and_b32_e32 v195, 0xffff0000, v185
	v_fma_f32 v2, v2, v138, v135
	v_fma_f32 v3, v3, v139, v135
	v_mul_f32_e32 v2, v2, v194
	v_mul_f32_e32 v3, v3, v195
	v_cvt_pk_bf16_f32 v0, v0, v1
	v_cvt_pk_bf16_f32 v1, v2, v3
	global_store_dwordx2 v[156:157], v[0:1], off
	v_fma_f32 v4, v4, v140, v135
	v_lshlrev_b32_e32 v192, 16, v186
	v_and_b32_e32 v193, 0xffff0000, v186
	v_fma_f32 v5, v5, v141, v135
	v_mul_f32_e32 v4, v4, v192
	v_mul_f32_e32 v5, v5, v193
	v_lshlrev_b32_e32 v194, 16, v187
	v_and_b32_e32 v195, 0xffff0000, v187
	v_fma_f32 v6, v6, v142, v135
	v_fma_f32 v7, v7, v143, v135
	v_mul_f32_e32 v6, v6, v194
	v_mul_f32_e32 v7, v7, v195
	v_cvt_pk_bf16_f32 v4, v4, v5
	v_cvt_pk_bf16_f32 v5, v6, v7
	global_store_dwordx2 v[156:157], v[4:5], off offset:16
	v_fma_f32 v8, v8, v144, v135
	v_lshlrev_b32_e32 v192, 16, v188
	v_and_b32_e32 v193, 0xffff0000, v188
	v_fma_f32 v9, v9, v145, v135
	v_mul_f32_e32 v8, v8, v192
	v_mul_f32_e32 v9, v9, v193
	v_lshlrev_b32_e32 v194, 16, v189
	v_and_b32_e32 v195, 0xffff0000, v189
	v_fma_f32 v10, v10, v146, v135
	v_fma_f32 v11, v11, v147, v135
	v_mul_f32_e32 v10, v10, v194
	v_mul_f32_e32 v11, v11, v195
	v_cvt_pk_bf16_f32 v8, v8, v9
	v_cvt_pk_bf16_f32 v9, v10, v11
	global_store_dwordx2 v[156:157], v[8:9], off offset:32
	v_fma_f32 v12, v12, v148, v135
	v_lshlrev_b32_e32 v192, 16, v190
	v_and_b32_e32 v193, 0xffff0000, v190
	v_fma_f32 v13, v13, v149, v135
	v_mul_f32_e32 v12, v12, v192
	v_mul_f32_e32 v13, v13, v193
	v_lshlrev_b32_e32 v194, 16, v191
	v_and_b32_e32 v195, 0xffff0000, v191
	v_fma_f32 v14, v14, v150, v135
	v_fma_f32 v15, v15, v151, v135
	v_mul_f32_e32 v14, v14, v194
	v_mul_f32_e32 v15, v15, v195
	v_cvt_pk_bf16_f32 v12, v12, v13
	v_cvt_pk_bf16_f32 v13, v14, v15
	global_store_dwordx2 v[156:157], v[12:13], off offset:48
	s_barrier
	s_cbranch_scc1 .LBB0_1061
